# v33 row-loop load hoisting + grp0 attention far-tile loop software-pipelined (all waves map0 path, barrier after QK, fragment prefetch across iterations)
# speedup vs baseline: 1.0059x; 1.0059x over previous
.Lfa0x_shift_done:
	s_waitcnt lgkmcnt(15)
	v_mfma_f32_32x32x16_bf16 v[18:33], v[126:129], v[168:171], v[18:33]
	s_nop 4
	v_lshl_add_u64 v[204:205], s[48:49], 0, v[0:1]
	s_mov_b64 s[6:7], 0xef88000
	s_add_i32 s87, s74, s50
	v_lshl_add_u64 v[206:207], v[204:205], 0, s[6:7]
	s_mov_b32 m0, s87
	s_mov_b64 s[6:7], 0xef8a000
	global_load_lds_dwordx4 v[206:207], off
	ds_read_b64_tr_b16 v[168:169], v209 offset:8192
	ds_read_b64_tr_b16 v[170:171], v209 offset:8448
	v_exp_f32_e32 v82, v82
	v_exp_f32_e32 v83, v83
	s_waitcnt lgkmcnt(15)
	v_mfma_f32_32x32x16_bf16 v[50:65], v[126:129], v[172:175], v[50:65]
	ds_read_b64_tr_b16 v[172:173], v209 offset:8704
	ds_read_b64_tr_b16 v[174:175], v209 offset:8960
	v_add_u32_e32 v252, v208, v164
	ds_read_b128 v[220:223], v252
	v_exp_f32_e32 v84, v84
	v_exp_f32_e32 v85, v85
	v_add_f32_e32 v138, 0, v82
	v_add_f32_e32 v138, v83, v138
	s_waitcnt lgkmcnt(15)
	v_mfma_f32_32x32x16_bf16 v[34:49], v[126:129], v[176:179], v[34:49]
	v_lshl_add_u64 v[204:205], v[204:205], 0, s[6:7]
	s_add_i32 m0, s87, 0x2000
	s_nop 0
	global_load_lds_dwordx4 v[204:205], off
	ds_read_b64_tr_b16 v[176:177], v209 offset:9216
	ds_read_b64_tr_b16 v[178:179], v209 offset:9472
	v_exp_f32_e32 v86, v86
	v_exp_f32_e32 v87, v87
	v_add_f32_e32 v138, v84, v138
	v_add_f32_e32 v138, v85, v138
	s_waitcnt lgkmcnt(15)
	v_mfma_f32_32x32x16_bf16 v[2:17], v[126:129], v[180:183], v[2:17]
	ds_read_b64_tr_b16 v[180:181], v209 offset:9728
	ds_read_b64_tr_b16 v[182:183], v209 offset:9984
	v_add_u32_e32 v252, v208, v165
	ds_read_b128 v[224:227], v252
	v_exp_f32_e32 v88, v88
	v_exp_f32_e32 v89, v89
	v_add_f32_e32 v138, v86, v138
	v_add_f32_e32 v138, v87, v138
	s_waitcnt lgkmcnt(15)
	v_mfma_f32_32x32x16_bf16 v[18:33], v[122:125], v[184:187], v[18:33]
	ds_read_b64_tr_b16 v[184:185], v209 offset:12288
	ds_read_b64_tr_b16 v[186:187], v209 offset:12544
	v_exp_f32_e32 v90, v90
	v_exp_f32_e32 v91, v91
	v_add_f32_e32 v138, v88, v138
	v_add_f32_e32 v138, v89, v138
	v_cvt_pk_bf16_f32 v126, v82, v83
	s_waitcnt lgkmcnt(15)
	v_mfma_f32_32x32x16_bf16 v[50:65], v[122:125], v[188:191], v[50:65]
	ds_read_b64_tr_b16 v[188:189], v209 offset:12800
	ds_read_b64_tr_b16 v[190:191], v209 offset:13056
	v_add_u32_e32 v252, v208, v166
	ds_read_b128 v[228:231], v252
	v_exp_f32_e32 v92, v92
	v_exp_f32_e32 v93, v93
	v_add_f32_e32 v138, v90, v138
	v_add_f32_e32 v138, v91, v138
	v_cvt_pk_bf16_f32 v127, v84, v85
	s_waitcnt lgkmcnt(15)
	v_mfma_f32_32x32x16_bf16 v[34:49], v[122:125], v[192:195], v[34:49]
	ds_read_b64_tr_b16 v[192:193], v209 offset:13312
	ds_read_b64_tr_b16 v[194:195], v209 offset:13568
	v_exp_f32_e32 v94, v94
	v_exp_f32_e32 v95, v95
	v_add_f32_e32 v138, v92, v138
	v_add_f32_e32 v138, v93, v138
	v_cvt_pk_bf16_f32 v128, v86, v87
	s_waitcnt lgkmcnt(15)
	v_mfma_f32_32x32x16_bf16 v[2:17], v[122:125], v[200:203], v[2:17]
	ds_read_b64_tr_b16 v[200:201], v209 offset:13824
	ds_read_b64_tr_b16 v[202:203], v209 offset:14080
	v_add_u32_e32 v252, v208, v167
	ds_read_b128 v[232:235], v252
	v_exp_f32_e32 v96, v96
	v_exp_f32_e32 v97, v97
	v_add_f32_e32 v138, v94, v138
	v_add_f32_e32 v138, v95, v138
	v_cvt_pk_bf16_f32 v129, v88, v89
	s_waitcnt lgkmcnt(15)
	v_mfma_f32_32x32x16_bf16 v[18:33], v[118:121], v[168:171], v[18:33]
	ds_read_b64_tr_b16 v[168:169], v210 offset:0
	ds_read_b64_tr_b16 v[170:171], v210 offset:256
	v_exp_f32_e32 v66, v66
	v_exp_f32_e32 v67, v67
	v_add_f32_e32 v138, v96, v138
	v_add_f32_e32 v138, v97, v138
	v_cvt_pk_bf16_f32 v122, v90, v91
	s_waitcnt lgkmcnt(15)
	v_mfma_f32_32x32x16_bf16 v[50:65], v[118:121], v[172:175], v[50:65]
	ds_read_b64_tr_b16 v[172:173], v210 offset:512
	ds_read_b64_tr_b16 v[174:175], v210 offset:768
	v_add_u32_e32 v252, v208, v164
	ds_read_b128 v[236:239], v252 offset:8192
	v_exp_f32_e32 v68, v68
	v_exp_f32_e32 v69, v69
	v_add_f32_e32 v138, v66, v138
	v_add_f32_e32 v138, v67, v138
	v_cvt_pk_bf16_f32 v123, v92, v93
	s_waitcnt lgkmcnt(15)
	v_mfma_f32_32x32x16_bf16 v[34:49], v[118:121], v[176:179], v[34:49]
	ds_read_b64_tr_b16 v[176:177], v210 offset:1024
	ds_read_b64_tr_b16 v[178:179], v210 offset:1280
	v_exp_f32_e32 v70, v70
	v_exp_f32_e32 v71, v71
	v_add_f32_e32 v138, v68, v138
	v_add_f32_e32 v138, v69, v138
	v_cvt_pk_bf16_f32 v124, v94, v95
	s_waitcnt lgkmcnt(15)
	v_mfma_f32_32x32x16_bf16 v[2:17], v[118:121], v[180:183], v[2:17]
	ds_read_b64_tr_b16 v[180:181], v210 offset:1536
	ds_read_b64_tr_b16 v[182:183], v210 offset:1792
	v_add_u32_e32 v252, v208, v165
	ds_read_b128 v[240:243], v252 offset:8192
	v_exp_f32_e32 v72, v72
	v_exp_f32_e32 v73, v73
	v_add_f32_e32 v138, v70, v138
	v_add_f32_e32 v138, v71, v138
	v_cvt_pk_bf16_f32 v125, v96, v97
	s_waitcnt lgkmcnt(15)
	v_mfma_f32_32x32x16_bf16 v[18:33], v[114:117], v[184:187], v[18:33]
	ds_read_b64_tr_b16 v[184:185], v210 offset:4096
	ds_read_b64_tr_b16 v[186:187], v210 offset:4352
	v_exp_f32_e32 v74, v74
	v_exp_f32_e32 v75, v75
	v_add_f32_e32 v138, v72, v138
	v_add_f32_e32 v138, v73, v138
	v_cvt_pk_bf16_f32 v118, v66, v67
	s_waitcnt lgkmcnt(15)
	v_mfma_f32_32x32x16_bf16 v[50:65], v[114:117], v[188:191], v[50:65]
	ds_read_b64_tr_b16 v[188:189], v210 offset:4608
	ds_read_b64_tr_b16 v[190:191], v210 offset:4864
	v_add_u32_e32 v252, v208, v166
	ds_read_b128 v[244:247], v252 offset:8192
	v_exp_f32_e32 v76, v76
	v_exp_f32_e32 v77, v77
	v_add_f32_e32 v138, v74, v138
	v_add_f32_e32 v138, v75, v138
	v_cvt_pk_bf16_f32 v119, v68, v69
	s_waitcnt lgkmcnt(15)
	v_mfma_f32_32x32x16_bf16 v[34:49], v[114:117], v[192:195], v[34:49]
	ds_read_b64_tr_b16 v[192:193], v210 offset:5120
	ds_read_b64_tr_b16 v[194:195], v210 offset:5376
	v_exp_f32_e32 v78, v78
	v_exp_f32_e32 v79, v79
	v_add_f32_e32 v138, v76, v138
	v_add_f32_e32 v138, v77, v138
	v_cvt_pk_bf16_f32 v120, v70, v71
	s_waitcnt lgkmcnt(15)
	v_mfma_f32_32x32x16_bf16 v[2:17], v[114:117], v[200:203], v[2:17]
	ds_read_b64_tr_b16 v[200:201], v210 offset:5632
	ds_read_b64_tr_b16 v[202:203], v210 offset:5888
	v_add_u32_e32 v252, v208, v167
	ds_read_b128 v[248:251], v252 offset:8192
	v_exp_f32_e32 v80, v80
	v_exp_f32_e32 v81, v81
	v_add_f32_e32 v138, v78, v138
	v_add_f32_e32 v138, v79, v138
	v_cvt_pk_bf16_f32 v121, v72, v73
	v_add_f32_e32 v138, v80, v138
	v_add_f32_e32 v138, v81, v138
	v_cvt_pk_bf16_f32 v114, v74, v75
	v_cvt_pk_bf16_f32 v115, v76, v77
	v_cvt_pk_bf16_f32 v116, v78, v79
	v_cvt_pk_bf16_f32 v117, v80, v81
	s_nop 0
	v_cmp_ge_f32_e32 vcc, s70, v138
	s_cmp_eq_u64 vcc, exec
	s_cbranch_scc0 .Lfa0x_slow
	v_add_f32_e32 v163, v163, v138
